# adds load hoisting in nsa_compress (pe loads) and nsa_token_prep (gain vector loads) to remove exposed round trips
# speedup vs baseline: 1.0025x; 1.0025x over previous
.LBB0_261:
	v_lshl_add_u64 v[8:9], v[78:79], 0, v[128:129]
	v_add_co_u32_e32 v10, vcc, s11, v8
	v_lshl_add_u64 v[12:13], v[76:77], 0, v[128:129]
	s_nop 0
	v_addc_co_u32_e32 v11, vcc, 0, v9, vcc
	s_mov_b32 s2, 0x11cc0000
	v_add_co_u32_e32 v14, vcc, s2, v12
	s_mov_b32 s2, 0x11cd0000
	s_nop 0
	v_addc_co_u32_e32 v15, vcc, 0, v13, vcc
	v_add_co_u32_e32 v16, vcc, s2, v12
	s_mov_b32 s2, 0x11ce0000
	s_nop 0
	v_addc_co_u32_e32 v17, vcc, 0, v13, vcc
	v_add_co_u32_e32 v106, vcc, s2, v12
	s_mov_b32 s2, 0x11cf0000
	s_nop 0
	v_addc_co_u32_e32 v107, vcc, 0, v13, vcc
	v_add_co_u32_e32 v12, vcc, s2, v12
	s_mov_b32 s2, 0x4001000
	s_nop 0
	v_addc_co_u32_e32 v13, vcc, 0, v13, vcc
	v_add_co_u32_e32 v8, vcc, s2, v8
	global_load_dwordx4 v[86:89], v[10:11], off
	s_nop 0
	v_addc_co_u32_e32 v9, vcc, 0, v9, vcc
	global_load_dwordx4 v[90:93], v[14:15], off
	global_load_dwordx4 v[94:97], v[16:17], off
	global_load_dwordx4 v[98:101], v[106:107], off
	global_load_dwordx4 v[102:105], v[12:13], off
	global_load_dwordx4 v[72:75], v[10:11], off offset:64
	global_load_dwordx4 v[56:59], v[14:15], off offset:64
	global_load_dwordx4 v[60:63], v[16:17], off offset:64
	global_load_dwordx4 v[64:67], v[106:107], off offset:64
	global_load_dwordx4 v[68:71], v[12:13], off offset:64
	global_load_dwordx4 v[52:55], v[8:9], off offset:2048
	global_load_dwordx4 v[36:39], v[14:15], off offset:128
	global_load_dwordx4 v[40:43], v[16:17], off offset:128
	global_load_dwordx4 v[44:47], v[106:107], off offset:128
	global_load_dwordx4 v[48:51], v[12:13], off offset:128
	global_load_dwordx4 v[24:27], v[8:9], off offset:2112
	global_load_dwordx4 v[20:23], v[14:15], off offset:192
	s_nop 0
	global_load_dwordx4 v[16:19], v[16:17], off offset:192
	s_nop 0
	global_load_dwordx4 v[8:11], v[106:107], off offset:192
	s_nop 0
	global_load_dwordx4 v[12:15], v[12:13], off offset:192
	s_nop 0
	global_load_dwordx4 v[106:109], v[80:81], off offset:-392
	global_load_dwordx4 v[110:113], v[80:81], off offset:-408
	global_load_dwordx4 v[130:133], v[80:81], off offset:-264
	global_load_dwordx4 v[134:137], v[80:81], off offset:-280
	global_load_dwordx4 v[138:141], v[80:81], off offset:-136
	global_load_dwordx4 v[142:145], v[80:81], off offset:-152
	global_load_dwordx4 v[146:149], v[80:81], off offset:-8
	global_load_dwordx4 v[150:153], v[80:81], off offset:-24
	s_add_i32 s27, s27, 4
	v_lshl_add_u64 v[76:77], v[76:77], 0, s[34:35]
	v_lshl_add_u64 v[78:79], v[78:79], 0, s[28:29]
	s_cmp_gt_u32 s27, 59
	s_waitcnt vmcnt(27)
	v_lshlrev_b32_e32 v114, 16, v86
	v_and_b32_e32 v115, 0xffff0000, v86
	s_waitcnt vmcnt(0)
	v_pk_add_f32 v[110:111], v[110:111], v[114:115]
	s_nop 0
	v_cvt_pk_bf16_f32 v86, v110, v111
	v_lshlrev_b32_e32 v110, 16, v87
	v_and_b32_e32 v111, 0xffff0000, v87
	v_pk_add_f32 v[110:111], v[112:113], v[110:111]
	s_nop 0
	v_cvt_pk_bf16_f32 v87, v110, v111
	v_lshlrev_b32_e32 v110, 16, v88
	v_and_b32_e32 v111, 0xffff0000, v88
	v_pk_add_f32 v[106:107], v[106:107], v[110:111]
	s_nop 0
	v_cvt_pk_bf16_f32 v88, v106, v107
	v_lshlrev_b32_e32 v106, 16, v89
	v_and_b32_e32 v107, 0xffff0000, v89
	v_pk_add_f32 v[106:107], v[108:109], v[106:107]
	s_nop 0
	v_cvt_pk_bf16_f32 v89, v106, v107
	s_nop 1
	v_mfma_f32_16x16x32_bf16 v[32:35], v[86:89], v[90:93], v[32:35]
	v_mfma_f32_16x16x32_bf16 v[28:31], v[86:89], v[94:97], v[28:31]
	v_lshlrev_b32_e32 v94, 16, v72
	v_and_b32_e32 v95, 0xffff0000, v72
	v_mfma_f32_16x16x32_bf16 v[4:7], v[86:89], v[98:101], v[4:7]
	v_mfma_f32_16x16x32_bf16 v[0:3], v[86:89], v[102:105], v[0:3]
	v_pk_add_f32 v[90:91], v[134:135], v[94:95]
	s_nop 0
	v_cvt_pk_bf16_f32 v72, v90, v91
	v_lshlrev_b32_e32 v90, 16, v73
	v_and_b32_e32 v91, 0xffff0000, v73
	v_pk_add_f32 v[90:91], v[136:137], v[90:91]
	s_nop 0
	v_cvt_pk_bf16_f32 v73, v90, v91
	v_lshlrev_b32_e32 v90, 16, v74
	v_and_b32_e32 v91, 0xffff0000, v74
	v_pk_add_f32 v[86:87], v[130:131], v[90:91]
	s_nop 0
	v_cvt_pk_bf16_f32 v74, v86, v87
	v_lshlrev_b32_e32 v86, 16, v75
	v_and_b32_e32 v87, 0xffff0000, v75
	v_pk_add_f32 v[86:87], v[132:133], v[86:87]
	s_nop 0
	v_cvt_pk_bf16_f32 v75, v86, v87
	s_nop 1
	v_mfma_f32_16x16x32_bf16 v[32:35], v[72:75], v[56:59], v[32:35]
	v_mfma_f32_16x16x32_bf16 v[56:59], v[72:75], v[60:63], v[28:31]
	v_mfma_f32_16x16x32_bf16 v[60:63], v[72:75], v[64:67], v[4:7]
	s_nop 1
	v_lshlrev_b32_e32 v28, 16, v52
	v_and_b32_e32 v29, 0xffff0000, v52
	v_mfma_f32_16x16x32_bf16 v[64:67], v[72:75], v[68:71], v[0:3]
	s_nop 2
	v_pk_add_f32 v[4:5], v[142:143], v[28:29]
	s_nop 0
	v_cvt_pk_bf16_f32 v52, v4, v5
	v_lshlrev_b32_e32 v4, 16, v53
	v_and_b32_e32 v5, 0xffff0000, v53
	v_pk_add_f32 v[4:5], v[144:145], v[4:5]
	s_nop 0
	v_cvt_pk_bf16_f32 v53, v4, v5
	v_lshlrev_b32_e32 v4, 16, v54
	v_and_b32_e32 v5, 0xffff0000, v54
	v_pk_add_f32 v[0:1], v[138:139], v[4:5]
	s_nop 0
	v_cvt_pk_bf16_f32 v54, v0, v1
	v_lshlrev_b32_e32 v0, 16, v55
	v_and_b32_e32 v1, 0xffff0000, v55
	v_pk_add_f32 v[0:1], v[140:141], v[0:1]
	s_nop 0
	v_cvt_pk_bf16_f32 v55, v0, v1
	s_nop 1
	v_mfma_f32_16x16x32_bf16 v[28:31], v[52:55], v[36:39], v[32:35]
	v_mfma_f32_16x16x32_bf16 v[4:7], v[52:55], v[40:43], v[56:59]
	s_nop 1
	v_lshl_add_u64 v[80:81], v[80:81], 0, s[44:45]
	v_mfma_f32_16x16x32_bf16 v[0:3], v[52:55], v[44:47], v[60:63]
	v_lshlrev_b32_e32 v44, 16, v24
	v_and_b32_e32 v45, 0xffff0000, v24
	v_pk_add_f32 v[40:41], v[150:151], v[44:45]
	s_nop 0
	v_cvt_pk_bf16_f32 v24, v40, v41
	v_lshlrev_b32_e32 v40, 16, v25
	v_and_b32_e32 v41, 0xffff0000, v25
	v_pk_add_f32 v[40:41], v[152:153], v[40:41]
	v_mfma_f32_16x16x32_bf16 v[36:39], v[52:55], v[48:51], v[64:67]
	v_cvt_pk_bf16_f32 v25, v40, v41
	v_lshlrev_b32_e32 v40, 16, v26
	v_and_b32_e32 v41, 0xffff0000, v26
	v_pk_add_f32 v[32:33], v[146:147], v[40:41]
	s_nop 0
	v_cvt_pk_bf16_f32 v26, v32, v33
	v_lshlrev_b32_e32 v32, 16, v27
	v_and_b32_e32 v33, 0xffff0000, v27
	v_pk_add_f32 v[32:33], v[148:149], v[32:33]
	s_nop 0
	v_cvt_pk_bf16_f32 v27, v32, v33
	s_nop 1
	v_mfma_f32_16x16x32_bf16 v[32:35], v[24:27], v[20:23], v[28:31]
	v_mfma_f32_16x16x32_bf16 v[28:31], v[24:27], v[16:19], v[4:7]
	v_mfma_f32_16x16x32_bf16 v[4:7], v[24:27], v[8:11], v[0:3]
	v_mfma_f32_16x16x32_bf16 v[0:3], v[24:27], v[12:15], v[36:39]
	s_cbranch_scc0 .LBB0_261
	s_nop 3
	v_mul_f32_e32 v8, 0x3d372713, v32
	v_mul_f32_e32 v8, v32, v8
	v_fma_f32 v8, v32, v8, v32
	v_mul_f32_e32 v11, 0x3f4c422a, v8
	s_mov_b32 s2, 0x3f200000
	v_cmp_nlt_f32_e64 s[2:3], |v11|, s2
	s_and_saveexec_b64 s[28:29], s[2:3]
	s_xor_b64 s[44:45], exec, s[28:29]
	s_cbranch_execz .LBB0_264
	v_add_f32_e64 v8, |v11|, |v11|
	v_mul_f32_e32 v9, 0x3fb8aa3b, v8
	v_rndne_f32_e32 v10, v9
	s_mov_b32 s2, 0x3fb8aa3b
	v_sub_f32_e32 v12, v9, v10
	v_fma_f32 v9, v8, s2, -v9
	v_fmac_f32_e32 v9, 0x32a5705f, v8
	v_add_f32_e32 v9, v12, v9
	v_cvt_i32_f32_e32 v10, v10
	v_exp_f32_e32 v9, v9
	s_mov_b32 s2, 0xc2ce8ed0
	v_cmp_ngt_f32_e32 vcc, s2, v8
	s_mov_b32 s2, 0x42b17218
	v_ldexp_f32 v9, v9, v10
	v_cndmask_b32_e32 v9, 0, v9, vcc
	v_cmp_nlt_f32_e32 vcc, s2, v8
	s_nop 1
	v_cndmask_b32_e32 v8, v228, v9, vcc
	v_add_f32_e32 v8, 1.0, v8
	v_rcp_f32_e32 v8, v8
	s_nop 0
	v_fma_f32 v12, v8, -2.0, 1.0

.LBB0_350:
	s_or_b64 exec, exec, s[50:51]
	v_cvt_pk_bf16_f32 v58, v78, v79
	v_cvt_pk_bf16_f32 v59, v76, v77
	v_cvt_pk_bf16_f32 v60, v74, v75
	v_cvt_pk_bf16_f32 v61, v72, v69
	global_store_dwordx4 v[6:7], v[58:61], off
	v_mov_b32_e32 v57, v56
	v_pk_mul_f32 v[54:55], v[56:57], v[54:55]
	v_cvt_pk_bf16_f32 v58, v62, v63
	v_cvt_pk_bf16_f32 v59, v64, v65
	v_cvt_pk_bf16_f32 v60, v66, v67
	v_cvt_pk_bf16_f32 v61, v70, v68
	global_store_dwordx4 v[6:7], v[58:61], off offset:16
	v_pk_mul_f32 v[52:53], v[56:57], v[52:53]
	v_pk_mul_f32 v[50:51], v[56:57], v[50:51]
	v_pk_mul_f32 v[48:49], v[56:57], v[48:49]
	v_pk_mul_f32 v[46:47], v[56:57], v[46:47]
	v_pk_mul_f32 v[44:45], v[56:57], v[44:45]
	v_pk_mul_f32 v[42:43], v[56:57], v[42:43]
	v_pk_mul_f32 v[40:41], v[56:57], v[40:41]
	v_pk_mul_f32 v[38:39], v[56:57], v[38:39]
	v_pk_mul_f32 v[36:37], v[56:57], v[36:37]
	v_pk_mul_f32 v[34:35], v[56:57], v[34:35]
	v_pk_mul_f32 v[32:33], v[56:57], v[32:33]
	v_pk_mul_f32 v[30:31], v[56:57], v[30:31]
	v_pk_mul_f32 v[28:29], v[56:57], v[28:29]
	v_pk_mul_f32 v[26:27], v[56:57], v[26:27]
	v_pk_mul_f32 v[24:25], v[56:57], v[24:25]
	v_pk_mul_f32 v[22:23], v[56:57], v[22:23]
	v_pk_mul_f32 v[20:21], v[56:57], v[20:21]
	v_pk_mul_f32 v[18:19], v[56:57], v[18:19]
	v_pk_mul_f32 v[16:17], v[56:57], v[16:17]
	s_movk_i32 s2, 0x1ff
	v_add_u32_e32 v1, 0x100, v2
	v_cmp_lt_i32_e32 vcc, s2, v2
	v_pk_mul_f32 v[2:3], v[56:57], v[8:9]
	v_pk_mul_f32 v[8:9], v[56:57], v[12:13]
	v_add_u32_e32 v0, 0x4000, v0
	s_or_b64 s[48:49], vcc, s[48:49]
	v_pk_mul_f32 v[54:55], v[54:55], v[156:157]
	v_pk_mul_f32 v[52:53], v[52:53], v[158:159]
	v_pk_mul_f32 v[50:51], v[50:51], v[160:161]
	v_pk_mul_f32 v[58:59], v[48:49], v[162:163]
	v_cvt_pk_bf16_f32 v48, v54, v55
	v_cvt_pk_bf16_f32 v49, v52, v53
	v_cvt_pk_bf16_f32 v50, v50, v51
	v_cvt_pk_bf16_f32 v51, v58, v59
	global_store_dwordx4 v[6:7], v[48:51], off offset:32
	v_pk_mul_f32 v[46:47], v[46:47], v[164:165]
	v_pk_mul_f32 v[44:45], v[44:45], v[166:167]
	v_pk_mul_f32 v[42:43], v[42:43], v[168:169]
	v_pk_mul_f32 v[48:49], v[40:41], v[170:171]
	v_cvt_pk_bf16_f32 v40, v46, v47
	v_cvt_pk_bf16_f32 v41, v44, v45
	v_cvt_pk_bf16_f32 v42, v42, v43
	v_cvt_pk_bf16_f32 v43, v48, v49
	global_store_dwordx4 v[6:7], v[40:43], off offset:48
	v_pk_mul_f32 v[38:39], v[38:39], v[172:173]
	v_pk_mul_f32 v[36:37], v[36:37], v[174:175]
	v_pk_mul_f32 v[34:35], v[34:35], v[176:177]
	v_pk_mul_f32 v[40:41], v[32:33], v[178:179]
	v_cvt_pk_bf16_f32 v32, v38, v39
	v_cvt_pk_bf16_f32 v33, v36, v37
	v_cvt_pk_bf16_f32 v34, v34, v35
	v_cvt_pk_bf16_f32 v35, v40, v41
	global_store_dwordx4 v[6:7], v[32:35], off offset:64
	v_pk_mul_f32 v[30:31], v[30:31], v[180:181]
	v_pk_mul_f32 v[28:29], v[28:29], v[182:183]
	v_pk_mul_f32 v[26:27], v[26:27], v[184:185]
	v_pk_mul_f32 v[32:33], v[24:25], v[186:187]
	v_cvt_pk_bf16_f32 v24, v30, v31
	v_cvt_pk_bf16_f32 v25, v28, v29
	v_cvt_pk_bf16_f32 v26, v26, v27
	v_cvt_pk_bf16_f32 v27, v32, v33
	global_store_dwordx4 v[6:7], v[24:27], off offset:80
	v_pk_mul_f32 v[22:23], v[22:23], v[188:189]
	v_pk_mul_f32 v[20:21], v[20:21], v[190:191]
	v_pk_mul_f32 v[18:19], v[18:19], v[192:193]
	v_pk_mul_f32 v[24:25], v[16:17], v[194:195]
	v_cvt_pk_bf16_f32 v16, v22, v23
	v_cvt_pk_bf16_f32 v17, v20, v21
	v_cvt_pk_bf16_f32 v18, v18, v19
	v_cvt_pk_bf16_f32 v19, v24, v25
	global_store_dwordx4 v[6:7], v[16:19], off offset:96
	v_pk_mul_f32 v[4:5], v[56:57], v[10:11]
	v_pk_mul_f32 v[10:11], v[56:57], v[14:15]
	v_pk_mul_f32 v[2:3], v[2:3], v[196:197]
	v_pk_mul_f32 v[4:5], v[4:5], v[198:199]
	v_pk_mul_f32 v[8:9], v[8:9], v[200:201]
	v_pk_mul_f32 v[10:11], v[10:11], v[202:203]
	v_cvt_pk_bf16_f32 v2, v2, v3
	v_cvt_pk_bf16_f32 v3, v4, v5
	v_cvt_pk_bf16_f32 v4, v8, v9
	v_cvt_pk_bf16_f32 v5, v10, v11
	global_store_dwordx4 v[6:7], v[2:5], off offset:112
	s_nop 1
	v_mov_b32_e32 v2, v1
	s_andn2_b64 exec, exec, s[48:49]
	s_cbranch_execz .LBB0_421

.LBB0_359:
	s_or_b64 exec, exec, s[50:51]
	v_ashrrev_i32_e32 v7, 31, v6
	v_lshl_add_u64 v[60:61], v[6:7], 0, s[84:85]
	v_mov_b64_e32 v[6:7], s[42:43]
	v_mad_u64_u32 v[6:7], s[2:3], v60, s10, v[6:7]
	v_mad_i32_i24 v7, v61, s10, v7
	v_lshl_add_u64 v[6:7], v[128:129], 1, v[6:7]
	global_load_dwordx4 v[62:65], v[6:7], off
	global_load_dwordx4 v[66:69], v[6:7], off offset:16
	global_load_dwordx4 v[8:11], v[6:7], off offset:32
	global_load_dwordx4 v[12:15], v[6:7], off offset:48
	global_load_dwordx4 v[16:19], v[6:7], off offset:64
	global_load_dwordx4 v[20:23], v[6:7], off offset:80
	global_load_dwordx4 v[70:73], v[6:7], off offset:96
	global_load_dwordx4 v[74:77], v[6:7], off offset:112
	s_mov_b32 s2, 0x800000
	s_waitcnt vmcnt(7)
	v_and_b32_e32 v141, 0xffff0000, v62
	v_lshlrev_b32_e32 v140, 16, v62
	s_waitcnt vmcnt(5)
	v_and_b32_e32 v55, 0xffff0000, v8
	v_lshlrev_b32_e32 v54, 16, v8
	v_and_b32_e32 v53, 0xffff0000, v9
	v_lshlrev_b32_e32 v52, 16, v9
	v_and_b32_e32 v51, 0xffff0000, v10
	v_lshlrev_b32_e32 v50, 16, v10
	v_and_b32_e32 v49, 0xffff0000, v11
	v_lshlrev_b32_e32 v48, 16, v11
	s_waitcnt vmcnt(4)
	v_and_b32_e32 v47, 0xffff0000, v12
	v_lshlrev_b32_e32 v46, 16, v12
	v_and_b32_e32 v45, 0xffff0000, v13
	v_lshlrev_b32_e32 v44, 16, v13
	v_and_b32_e32 v43, 0xffff0000, v14
	v_lshlrev_b32_e32 v42, 16, v14
	v_and_b32_e32 v41, 0xffff0000, v15
	v_lshlrev_b32_e32 v40, 16, v15
	s_waitcnt vmcnt(3)
	v_and_b32_e32 v39, 0xffff0000, v16
	v_lshlrev_b32_e32 v38, 16, v16
	v_and_b32_e32 v37, 0xffff0000, v17
	v_lshlrev_b32_e32 v36, 16, v17
	v_and_b32_e32 v35, 0xffff0000, v18
	v_lshlrev_b32_e32 v34, 16, v18
	v_and_b32_e32 v33, 0xffff0000, v19
	v_lshlrev_b32_e32 v32, 16, v19
	s_waitcnt vmcnt(2)
	v_and_b32_e32 v31, 0xffff0000, v20
	v_lshlrev_b32_e32 v30, 16, v20
	v_and_b32_e32 v29, 0xffff0000, v21
	v_lshlrev_b32_e32 v28, 16, v21
	v_and_b32_e32 v27, 0xffff0000, v22
	v_lshlrev_b32_e32 v26, 16, v22
	v_and_b32_e32 v25, 0xffff0000, v23
	v_lshlrev_b32_e32 v24, 16, v23
	s_waitcnt vmcnt(1)
	v_and_b32_e32 v23, 0xffff0000, v70
	v_lshlrev_b32_e32 v22, 16, v70
	v_and_b32_e32 v21, 0xffff0000, v71
	v_lshlrev_b32_e32 v20, 16, v71
	v_and_b32_e32 v19, 0xffff0000, v72
	v_lshlrev_b32_e32 v18, 16, v72
	v_and_b32_e32 v17, 0xffff0000, v73
	v_lshlrev_b32_e32 v16, 16, v73
	s_waitcnt vmcnt(0)
	v_and_b32_e32 v9, 0xffff0000, v74
	v_lshlrev_b32_e32 v8, 16, v74
	v_and_b32_e32 v11, 0xffff0000, v75
	v_lshlrev_b32_e32 v10, 16, v75
	v_and_b32_e32 v13, 0xffff0000, v76
	v_lshlrev_b32_e32 v12, 16, v76
	v_and_b32_e32 v15, 0xffff0000, v77
	v_lshlrev_b32_e32 v14, 16, v77
	global_load_dwordx4 v[82:85], v[4:5], off offset:48
	global_load_dwordx4 v[86:89], v[4:5], off offset:32
	global_load_dwordx4 v[70:73], v[4:5], off offset:16
	global_load_dwordx4 v[74:77], v[4:5], off
	global_load_dwordx4 v[156:159], v[4:5], off offset:64
	global_load_dwordx4 v[160:163], v[4:5], off offset:80
	global_load_dwordx4 v[164:167], v[4:5], off offset:96
	global_load_dwordx4 v[168:171], v[4:5], off offset:112
	global_load_dwordx4 v[172:175], v[4:5], off offset:128
	global_load_dwordx4 v[176:179], v[4:5], off offset:144
	global_load_dwordx4 v[180:183], v[4:5], off offset:160
	global_load_dwordx4 v[184:187], v[4:5], off offset:176
	global_load_dwordx4 v[188:191], v[4:5], off offset:192
	global_load_dwordx4 v[192:195], v[4:5], off offset:208
	global_load_dwordx4 v[196:199], v[4:5], off offset:224
	global_load_dwordx4 v[200:203], v[4:5], off offset:240
	v_pk_mul_f32 v[142:143], v[140:141], v[140:141]
	v_and_b32_e32 v149, 0xffff0000, v63
	v_lshlrev_b32_e32 v148, 16, v63
	v_pk_mul_f32 v[62:63], v[148:149], v[148:149]
	v_add_f32_e32 v59, v142, v143
	v_lshlrev_b32_e32 v1, 16, v65
	v_and_b32_e32 v137, 0xffff0000, v65
	v_and_b32_e32 v65, 0xffff0000, v64
	v_lshlrev_b32_e32 v64, 16, v64
	v_add_f32_e32 v59, v59, v62
	v_pk_mul_f32 v[152:153], v[64:65], v[64:65]
	v_add_f32_e32 v59, v59, v63
	v_add_f32_e32 v59, v59, v152
	v_and_b32_e32 v136, 0xffff0000, v69
	v_add_f32_e32 v59, v59, v153
	v_pk_mul_f32 v[138:139], v[136:137], v[136:137]
	v_and_b32_e32 v145, 0xffff0000, v66
	v_lshlrev_b32_e32 v144, 16, v66
	v_fmac_f32_e32 v59, v1, v1
	v_pk_mul_f32 v[146:147], v[144:145], v[144:145]
	v_add_f32_e32 v59, v59, v139
	v_and_b32_e32 v151, 0xffff0000, v67
	v_lshlrev_b32_e32 v150, 16, v67
	v_add_f32_e32 v59, v59, v146
	v_pk_mul_f32 v[66:67], v[150:151], v[150:151]
	v_add_f32_e32 v59, v59, v147
	v_and_b32_e32 v155, 0xffff0000, v68
	v_lshlrev_b32_e32 v154, 16, v68
	v_add_f32_e32 v59, v59, v66
	v_lshlrev_b32_e32 v3, 16, v69
	v_pk_mul_f32 v[68:69], v[154:155], v[154:155]
	v_add_f32_e32 v59, v59, v67
	v_add_f32_e32 v59, v59, v68
	v_add_f32_e32 v59, v59, v69
	v_fmac_f32_e32 v59, v3, v3
	v_pk_mul_f32 v[56:57], v[54:55], v[54:55]
	v_add_f32_e32 v59, v59, v138
	v_add_f32_e32 v56, v59, v56
	v_pk_mul_f32 v[78:79], v[52:53], v[52:53]
	v_add_f32_e32 v56, v56, v57
	v_add_f32_e32 v56, v56, v78
	v_pk_mul_f32 v[90:91], v[50:51], v[50:51]
	v_add_f32_e32 v56, v56, v79
	v_add_f32_e32 v56, v56, v90
	v_pk_mul_f32 v[92:93], v[48:49], v[48:49]
	v_add_f32_e32 v56, v56, v91
	v_add_f32_e32 v56, v56, v92
	v_pk_mul_f32 v[94:95], v[46:47], v[46:47]
	v_add_f32_e32 v56, v56, v93
	v_add_f32_e32 v56, v56, v94
	v_pk_mul_f32 v[96:97], v[44:45], v[44:45]
	v_add_f32_e32 v56, v56, v95
	v_add_f32_e32 v56, v56, v96
	v_pk_mul_f32 v[98:99], v[42:43], v[42:43]
	v_add_f32_e32 v56, v56, v97
	v_add_f32_e32 v56, v56, v98
	v_pk_mul_f32 v[100:101], v[40:41], v[40:41]
	v_add_f32_e32 v56, v56, v99
	v_add_f32_e32 v56, v56, v100
	v_pk_mul_f32 v[102:103], v[38:39], v[38:39]
	v_add_f32_e32 v56, v56, v101
	v_add_f32_e32 v56, v56, v102
	v_pk_mul_f32 v[104:105], v[36:37], v[36:37]
	v_add_f32_e32 v56, v56, v103
	v_add_f32_e32 v56, v56, v104
	v_pk_mul_f32 v[106:107], v[34:35], v[34:35]
	v_add_f32_e32 v56, v56, v105
	v_add_f32_e32 v56, v56, v106
	v_pk_mul_f32 v[108:109], v[32:33], v[32:33]
	v_add_f32_e32 v56, v56, v107
	v_add_f32_e32 v56, v56, v108
	v_pk_mul_f32 v[110:111], v[30:31], v[30:31]
	v_add_f32_e32 v56, v56, v109
	v_add_f32_e32 v56, v56, v110
	v_pk_mul_f32 v[112:113], v[28:29], v[28:29]
	v_add_f32_e32 v56, v56, v111
	v_add_f32_e32 v56, v56, v112
	v_pk_mul_f32 v[114:115], v[26:27], v[26:27]
	v_add_f32_e32 v56, v56, v113
	v_add_f32_e32 v56, v56, v114
	v_pk_mul_f32 v[116:117], v[24:25], v[24:25]
	v_add_f32_e32 v56, v56, v115
	v_add_f32_e32 v56, v56, v116
	v_pk_mul_f32 v[118:119], v[22:23], v[22:23]
	v_add_f32_e32 v56, v56, v117
	v_add_f32_e32 v56, v56, v118
	v_pk_mul_f32 v[120:121], v[20:21], v[20:21]
	v_add_f32_e32 v56, v56, v119
	v_add_f32_e32 v56, v56, v120
	v_pk_mul_f32 v[122:123], v[18:19], v[18:19]
	v_add_f32_e32 v56, v56, v121
	v_add_f32_e32 v56, v56, v122
	v_pk_mul_f32 v[124:125], v[16:17], v[16:17]
	v_add_f32_e32 v56, v56, v123
	v_add_f32_e32 v56, v56, v124
	v_pk_mul_f32 v[126:127], v[8:9], v[8:9]
	v_add_f32_e32 v56, v56, v125
	v_add_f32_e32 v56, v56, v126
	v_pk_mul_f32 v[130:131], v[10:11], v[10:11]
	v_add_f32_e32 v56, v56, v127
	v_add_f32_e32 v56, v56, v130
	v_pk_mul_f32 v[132:133], v[12:13], v[12:13]
	v_add_f32_e32 v56, v56, v131
	v_add_f32_e32 v56, v56, v132
	v_pk_mul_f32 v[134:135], v[14:15], v[14:15]
	v_add_f32_e32 v56, v56, v133
	v_add_f32_e32 v56, v56, v134
	v_add_f32_e32 v56, v56, v135
	v_fmamk_f32 v56, v56, 0x3c800000, v220
	v_mul_f32_e32 v57, 0x4b800000, v56
	v_cmp_gt_f32_e32 vcc, s2, v56
	s_waitcnt vmcnt(3)
	v_mov_b32_e32 v62, v85
	s_waitcnt vmcnt(1)
	v_mov_b32_e32 v63, v73
	v_cndmask_b32_e32 v56, v56, v57, vcc
	v_rsq_f32_e32 v56, v56
	s_nop 0
	v_mul_f32_e32 v57, 0x45800000, v56
	v_cndmask_b32_e32 v56, v56, v57, vcc
	v_pk_mul_f32 v[66:67], v[56:57], v[140:141] op_sel_hi:[0,1]
	v_pk_mul_f32 v[64:65], v[56:57], v[64:65] op_sel_hi:[0,1]
	s_waitcnt vmcnt(0)
	v_pk_mul_f32 v[78:79], v[74:75], v[66:67]
	v_pk_mul_f32 v[66:67], v[56:57], v[148:149] op_sel_hi:[0,1]
	v_pk_mul_f32 v[74:75], v[70:71], v[64:65]
	v_mul_f32_e32 v1, v56, v1
	v_pk_mul_f32 v[64:65], v[56:57], v[136:137] op_sel_hi:[0,1]
	v_pk_mul_f32 v[76:77], v[76:77], v[66:67]
	v_mul_f32_e32 v72, v72, v1
	v_pk_mul_f32 v[68:69], v[64:65], v[62:63]
	v_pk_mul_f32 v[62:63], v[56:57], v[144:145] op_sel_hi:[0,1]
	v_pk_mul_f32 v[64:65], v[56:57], v[150:151] op_sel_hi:[0,1]
	v_pk_mul_f32 v[66:67], v[56:57], v[154:155] op_sel_hi:[0,1]
	v_mul_f32_e32 v1, v56, v3
	v_pk_mul_f32 v[62:63], v[86:87], v[62:63]
	v_pk_mul_f32 v[64:65], v[88:89], v[64:65]
	v_pk_mul_f32 v[66:67], v[82:83], v[66:67]
	v_mul_f32_e32 v70, v1, v84
	v_cmp_lt_i32_e32 vcc, 7, v58
	s_and_saveexec_b64 s[50:51], vcc
	s_cbranch_execz .LBB0_350
	v_lshlrev_b64 v[58:59], 6, v[60:61]
	v_lshl_add_u64 v[90:91], s[46:47], 0, v[58:59]
	global_load_dwordx4 v[58:61], v[90:91], off offset:48
	global_load_dwordx4 v[82:85], v[90:91], off offset:32
	global_load_dwordx4 v[86:89], v[90:91], off offset:16
	s_nop 0
	global_load_dwordx4 v[90:93], v[90:91], off
	v_mov_b32_e32 v71, v68
	v_mov_b32_e32 v73, v69
	s_waitcnt vmcnt(2)
	v_pk_mul_f32 v[94:95], v[62:63], v[82:83]
	s_waitcnt vmcnt(0)
	v_pk_fma_f32 v[94:95], v[78:79], v[90:91], v[94:95] neg_lo:[0,0,1] neg_hi:[0,0,1]
	v_pk_mul_f32 v[78:79], v[78:79], v[82:83]
	s_nop 0
	v_pk_fma_f32 v[62:63], v[62:63], v[90:91], v[78:79]
	v_pk_mul_f32 v[78:79], v[64:65], v[84:85]
	s_nop 0
	v_pk_fma_f32 v[82:83], v[76:77], v[92:93], v[78:79] neg_lo:[0,0,1] neg_hi:[0,0,1]
	v_pk_mul_f32 v[76:77], v[76:77], v[84:85]
	v_mov_b32_e32 v78, v94
	v_pk_fma_f32 v[64:65], v[64:65], v[92:93], v[76:77]
	v_pk_mul_f32 v[76:77], v[66:67], v[58:59]
	v_pk_mul_f32 v[58:59], v[74:75], v[58:59]
	v_pk_fma_f32 v[84:85], v[74:75], v[86:87], v[76:77] neg_lo:[0,0,1] neg_hi:[0,0,1]
	v_pk_fma_f32 v[66:67], v[66:67], v[86:87], v[58:59]
	v_pk_mul_f32 v[58:59], v[70:71], v[60:61]
	v_mul_f32_e32 v70, v70, v88
	v_pk_fma_f32 v[58:59], v[72:73], v[88:89], v[58:59] neg_lo:[0,0,1] neg_hi:[0,0,1]
	v_mul_f32_e32 v72, v72, v60
	v_mov_b32_e32 v60, v89
	v_pk_mul_f32 v[60:61], v[68:69], v[60:61]
	v_mov_b32_e32 v79, v95
	v_mov_b32_e32 v71, v60
	v_mov_b32_e32 v73, v61
	v_pk_add_f32 v[70:71], v[70:71], v[72:73]
	v_mov_b32_e32 v76, v82
	v_mov_b32_e32 v77, v83
	v_mov_b32_e32 v74, v84
	v_mov_b32_e32 v75, v85
	v_mov_b32_e32 v72, v58
	v_mov_b32_e32 v69, v59
	v_mov_b32_e32 v68, v71
	s_branch .LBB0_350
